# up-GEMM epilogue: conv weights prefetched before the K-loop (2 dwords/lane) and broadcast by DPP row_newbcast; no vmcnt wait at epilogue start
# speedup vs baseline: 1.0034x; 1.0034x over previous
;     DEV bool operator()(f32x4 (&acc)[2][2][4][2], const Unit& u, int wr, int wc, int fr, int fq) const {
;         const int ch0 = u.pn * 128 + wc * 32 + 8 * fq;
;         float w[3][8];
; #pragma unroll
;         for (int k = 0; k < 3; ++k) { const f32x4 w0 = *(const f32x4*)(cw + k * DFF + ch0), w1 = *(const f32x4*)(cw + k * DFF + ch0 + 4);
; #pragma unroll
;             for (int j = 0; j < 4; ++j) { w[k][j] = w0[j]; w[k][4 + j] = w1[j]; } }
; template <bool ALIGN_EPI, class Epi, class Sched>
; DEV void gemm_phase(LAS unsigned char* lds, const Gemm g, const Sched& S, const Epi& E) {
;     ...
;         if (rst) {
; #pragma unroll
;         for (int a = 0; a < 2; ++a)
; #pragma unroll
;             for (int b = 0; b < 2; ++b)
; #pragma unroll
;                 for (int m = 0; m < 4; ++m)
; #pragma unroll
;                     for (int n = 0; n < 2; ++n) acc[a][b][m][n] = (f32x4){0.f, 0.f, 0.f, 0.f}; }
.LBB0_27:
	v_and_b32_e32 v3, 15, v213
	v_and_b32_e32 v4, 7, v3
	v_lshrrev_b32_e32 v3, 3, v3
	v_mul_u32_u24_e32 v3, 0xc00, v3
	s_lshl_b32 s48, s20, 7
	v_add3_u32 v4, v4, v229, s48
	v_add_lshl_u32 v3, v3, v4, 2
	v_lshlrev_b32_e32 v4, 2, v4
	v_add_u32_e32 v4, 0x6000, v4
	global_load_dword v246, v3, s[50:51]
	global_load_dword v247, v4, s[50:51]
	s_ashr_i32 s85, s84, 31
	s_lshl_b64 s[48:49], s[84:85], 19
	s_add_u32 s86, s34, s48
	s_addc_u32 s87, s35, s49
	s_and_b64 s[48:49], s[44:45], exec
	s_cselect_b32 s85, s87, s5
	s_cselect_b32 vcc_lo, s86, s4
	s_ashr_i32 s83, s82, 31
	s_lshl_b64 s[48:49], s[82:83], 19
	s_add_u32 s88, s38, s48
	s_addc_u32 s89, s39, s49
	s_and_b64 s[48:49], s[44:45], exec
	s_cselect_b32 s83, s89, s7
	s_cselect_b32 vcc_hi, s88, s6
	s_add_u32 s21, s6, 0x100
	v_mov_b32_e32 v2, 0
	s_addc_u32 s48, s7, 0
	s_mov_b32 s49, -2
	v_mov_b32_e32 v3, v2
	v_mov_b64_e32 v[4:5], 0
	v_mov_b64_e32 v[18:19], 0
	v_mov_b64_e32 v[20:21], 0
	v_mov_b64_e32 v[34:35], 0
	v_mov_b64_e32 v[36:37], 0
	v_mov_b64_e32 v[42:43], 0
	v_mov_b64_e32 v[44:45], 0
	v_mov_b64_e32 v[50:51], 0
	v_mov_b64_e32 v[52:53], 0
	v_mov_b64_e32 v[58:59], 0
	v_mov_b64_e32 v[60:61], 0
	v_mov_b64_e32 v[74:75], 0
	v_mov_b64_e32 v[76:77], 0
	v_mov_b64_e32 v[90:91], 0
	v_mov_b64_e32 v[92:93], 0
	v_mov_b64_e32 v[6:7], 0
	v_mov_b64_e32 v[8:9], 0
	v_mov_b64_e32 v[22:23], 0
	v_mov_b64_e32 v[24:25], 0
	v_mov_b64_e32 v[10:11], 0
	v_mov_b64_e32 v[12:13], 0
	v_mov_b64_e32 v[26:27], 0
	v_mov_b64_e32 v[28:29], 0
	v_mov_b64_e32 v[14:15], 0
	v_mov_b64_e32 v[16:17], 0
	v_mov_b64_e32 v[30:31], 0
	v_mov_b64_e32 v[32:33], 0
	v_mov_b64_e32 v[38:39], 0
	v_mov_b64_e32 v[40:41], 0
	v_mov_b64_e32 v[46:47], 0
	v_mov_b64_e32 v[48:49], 0
	v_mov_b64_e32 v[98:99], 0
	v_mov_b64_e32 v[100:101], 0
	v_mov_b64_e32 v[106:107], 0
	v_mov_b64_e32 v[108:109], 0
	v_mov_b64_e32 v[114:115], 0
	v_mov_b64_e32 v[116:117], 0
	v_mov_b64_e32 v[126:127], 0
	v_mov_b64_e32 v[128:129], 0
	v_mov_b64_e32 v[138:139], 0
	v_mov_b64_e32 v[140:141], 0
	v_mov_b64_e32 v[142:143], 0
	v_mov_b64_e32 v[144:145], 0
	v_mov_b64_e32 v[146:147], 0
	v_mov_b64_e32 v[148:149], 0
	v_mov_b64_e32 v[150:151], 0
	v_mov_b64_e32 v[152:153], 0
	v_mov_b64_e32 v[54:55], 0
	v_mov_b64_e32 v[56:57], 0
	v_mov_b64_e32 v[70:71], 0
	v_mov_b64_e32 v[72:73], 0
	v_mov_b64_e32 v[86:87], 0
	v_mov_b64_e32 v[88:89], 0
	v_mov_b64_e32 v[94:95], 0
	v_mov_b64_e32 v[96:97], 0
	v_mov_b64_e32 v[102:103], 0
	v_mov_b64_e32 v[104:105], 0
	v_mov_b64_e32 v[110:111], 0
	v_mov_b64_e32 v[112:113], 0
	v_mov_b64_e32 v[118:119], 0
	v_mov_b64_e32 v[120:121], 0
	v_mov_b64_e32 v[130:131], 0
	v_mov_b64_e32 v[132:133], 0

; #define LAS __attribute__((address_space(3)))
;     DEV bool operator()(f32x4 (&acc)[2][2][4][2], const Unit& u, int wr, int wc, int fr, int fq) const {
;         const int ch0 = u.pn * 128 + wc * 32 + 8 * fq;
;         float w[3][8];
; #pragma unroll
;         for (int k = 0; k < 3; ++k) { const f32x4 w0 = *(const f32x4*)(cw + k * DFF + ch0), w1 = *(const f32x4*)(cw + k * DFF + ch0 + 4);
; #pragma unroll
;             for (int j = 0; j < 4; ++j) { w[k][j] = w0[j]; w[k][4 + j] = w1[j]; } }
;         float p6[8], p7[8];
; #pragma unroll
;         for (int c = 0; c < 8; ++c) { p6[c] = __shfl_up(acc[1][0][2][c >> 2][c & 3], 1); p7[c] = __shfl_up(acc[1][0][3][c >> 2][c & 3], 1); }
;         LAS float* EX = (LAS float*)ex + (wc * 4 + fq) * 16;
;         if (wr == 0 && fr == 15) {
; #pragma unroll
;             for (int c = 0; c < 8; ++c) { EX[c] = acc[1][0][2][c >> 2][c & 3]; EX[8 + c] = acc[1][0][3][c >> 2][c & 3]; }
;         }
.LBB0_31:
	v_lshl_or_b32 v192, s20, 7, v229
	v_ashrrev_i32_e32 v193, 31, v192
	v_mov_b32_dpp v134, v246 row_newbcast:0 row_mask:0xf bank_mask:0xf
	v_mov_b32_dpp v135, v246 row_newbcast:1 row_mask:0xf bank_mask:0xf
	v_mov_b32_dpp v136, v246 row_newbcast:2 row_mask:0xf bank_mask:0xf
	v_mov_b32_dpp v137, v246 row_newbcast:3 row_mask:0xf bank_mask:0xf
	v_mov_b32_dpp v122, v246 row_newbcast:4 row_mask:0xf bank_mask:0xf
	v_mov_b32_dpp v123, v246 row_newbcast:5 row_mask:0xf bank_mask:0xf
	v_mov_b32_dpp v124, v246 row_newbcast:6 row_mask:0xf bank_mask:0xf
	v_mov_b32_dpp v125, v246 row_newbcast:7 row_mask:0xf bank_mask:0xf
	v_mov_b32_dpp v78, v246 row_newbcast:8 row_mask:0xf bank_mask:0xf
	v_mov_b32_dpp v79, v246 row_newbcast:9 row_mask:0xf bank_mask:0xf
	v_mov_b32_dpp v80, v246 row_newbcast:10 row_mask:0xf bank_mask:0xf
	v_mov_b32_dpp v81, v246 row_newbcast:11 row_mask:0xf bank_mask:0xf
	v_mov_b32_dpp v62, v246 row_newbcast:12 row_mask:0xf bank_mask:0xf
	v_mov_b32_dpp v63, v246 row_newbcast:13 row_mask:0xf bank_mask:0xf
	v_mov_b32_dpp v64, v246 row_newbcast:14 row_mask:0xf bank_mask:0xf
	v_mov_b32_dpp v65, v246 row_newbcast:15 row_mask:0xf bank_mask:0xf
	v_mov_b32_dpp v82, v247 row_newbcast:0 row_mask:0xf bank_mask:0xf
	v_mov_b32_dpp v83, v247 row_newbcast:1 row_mask:0xf bank_mask:0xf
	v_mov_b32_dpp v84, v247 row_newbcast:2 row_mask:0xf bank_mask:0xf
	v_mov_b32_dpp v85, v247 row_newbcast:3 row_mask:0xf bank_mask:0xf
	v_mov_b32_dpp v66, v247 row_newbcast:4 row_mask:0xf bank_mask:0xf
	v_mov_b32_dpp v67, v247 row_newbcast:5 row_mask:0xf bank_mask:0xf
	v_mov_b32_dpp v68, v247 row_newbcast:6 row_mask:0xf bank_mask:0xf
	v_mov_b32_dpp v69, v247 row_newbcast:7 row_mask:0xf bank_mask:0xf
	v_add_u32_e32 v154, -1, v213
	v_and_b32_e32 v155, 64, v213
	v_cmp_lt_i32_e32 vcc, v154, v155
	s_nop 1
	v_cndmask_b32_e32 v154, v154, v213, vcc
	v_lshlrev_b32_e32 v157, 2, v154
	ds_bpermute_b32 v166, v157, v26
	ds_bpermute_b32 v158, v157, v22
	ds_bpermute_b32 v167, v157, v27
	ds_bpermute_b32 v159, v157, v23
	ds_bpermute_b32 v168, v157, v28
	ds_bpermute_b32 v160, v157, v24
	ds_bpermute_b32 v169, v157, v29
	ds_bpermute_b32 v161, v157, v25
	ds_bpermute_b32 v162, v157, v10
	ds_bpermute_b32 v154, v157, v6
	ds_bpermute_b32 v163, v157, v11
	ds_bpermute_b32 v155, v157, v7
	ds_bpermute_b32 v164, v157, v12
	ds_bpermute_b32 v156, v157, v8
	ds_bpermute_b32 v165, v157, v13
	ds_bpermute_b32 v157, v157, v9
	s_and_saveexec_b64 s[4:5], s[54:55]
	s_cbranch_execz .LBB0_33
	ds_write_b128 v231, v[26:29]
	ds_write_b128 v231, v[22:25] offset:32
	ds_write_b128 v231, v[10:13] offset:16
	ds_write_b128 v231, v[6:9] offset:48

; DEV u32x4 pack8(const float (&f)[8]) { u32x4 w; w.x = cvt_pk_bf16(f[0], f[1]); w.y = cvt_pk_bf16(f[2], f[3]); w.z = cvt_pk_bf16(f[4], f[5]); w.w = cvt_pk_bf16(f[6], f[7]); return w; }
; DEV float gelu_t(float x) { const float u = x * (0.7978845608f + 0.0356774081f * x * x); return x * __builtin_amdgcn_rcpf(1.f + __builtin_amdgcn_exp2f(-2.885390082f * u)); }
;     DEV bool operator()(f32x4 (&acc)[2][2][4][2], const Unit& u, int wr, int wc, int fr, int fq) const {
;     ...
;         bf16_t* outp = ACT + ((size_t)u.pm * BM + (size_t)(16 * wr + fr) * 8) * DFF + ch0;
; #pragma unroll
;         for (int i = 0; i < 8; ++i) { float y[8];
; #pragma unroll
;             for (int c = 0; c < 8; ++c) {
;                 const float g0 = acc[i >> 2][0][i & 3][c >> 2][c & 3];
;                 const float gm1 = i >= 1 ? acc[(i - 1 < 0 ? 0 : i - 1) >> 2][0][(i - 1 < 0 ? 0 : i - 1) & 3][c >> 2][c & 3] : p7[c];
;                 const float gm2 = i >= 2 ? acc[(i - 2 < 0 ? 0 : i - 2) >> 2][0][(i - 2 < 0 ? 0 : i - 2) & 3][c >> 2][c & 3] : (i == 0 ? p6[c] : p7[c]);
;                 y[c] = gelu_t(w[0][c] * gm2 + w[1][c] * gm1 + w[2][c] * g0) * acc[i >> 2][1][i & 3][c >> 2][c & 3]; }
;             if (!(halo && i < 2)) *(u32x4*)(outp + (size_t)i * DFF) = pack8(y); }
.LBB0_37:
	s_or_b64 exec, exec, s[4:5]
	v_mov_b32_e32 v194, 0x180000
	v_mad_i64_i32 v[194:195], s[4:5], s64, v194, v[186:187]
	v_lshl_add_u64 v[192:193], v[192:193], 1, v[194:195]
	s_waitcnt lgkmcnt(0)
	v_mov_b32_e32 v236, 0x3d122279
	v_mov_b32_e32 v237, 0x3f4c422a
	v_mov_b32_e32 v238, 0xc038aa3b
	v_mov_b32_e32 v239, 1.0
	v_pk_mul_f32 v[202:203], v[134:135], v[166:167]
	v_pk_mul_f32 v[204:205], v[136:137], v[168:169]
	v_pk_mul_f32 v[206:207], v[122:123], v[162:163]
	v_pk_mul_f32 v[208:209], v[124:125], v[164:165]
	v_pk_fma_f32 v[202:203], v[78:79], v[158:159], v[202:203]
	v_pk_fma_f32 v[204:205], v[80:81], v[160:161], v[204:205]
	v_pk_fma_f32 v[206:207], v[62:63], v[154:155], v[206:207]
	v_pk_fma_f32 v[208:209], v[64:65], v[156:157], v[208:209]
	v_pk_fma_f32 v[194:195], v[82:83], v[130:131], v[202:203]
	v_pk_fma_f32 v[196:197], v[84:85], v[132:133], v[204:205]
	v_pk_fma_f32 v[198:199], v[66:67], v[118:119], v[206:207]
	v_pk_fma_f32 v[200:201], v[68:69], v[120:121], v[208:209]
	v_pk_mul_f32 v[202:203], v[194:195], v[236:237] op_sel_hi:[1,0]
	v_pk_mul_f32 v[204:205], v[196:197], v[236:237] op_sel_hi:[1,0]
	v_pk_mul_f32 v[206:207], v[198:199], v[236:237] op_sel_hi:[1,0]
	v_pk_mul_f32 v[208:209], v[200:201], v[236:237] op_sel_hi:[1,0]
	v_pk_fma_f32 v[202:203], v[194:195], v[202:203], v[236:237] op_sel:[0,0,1] op_sel_hi:[1,1,1]
	v_pk_fma_f32 v[204:205], v[196:197], v[204:205], v[236:237] op_sel:[0,0,1] op_sel_hi:[1,1,1]
	v_pk_fma_f32 v[206:207], v[198:199], v[206:207], v[236:237] op_sel:[0,0,1] op_sel_hi:[1,1,1]
	v_pk_fma_f32 v[208:209], v[200:201], v[208:209], v[236:237] op_sel:[0,0,1] op_sel_hi:[1,1,1]
	v_pk_mul_f32 v[202:203], v[194:195], v[202:203]
	v_pk_mul_f32 v[204:205], v[196:197], v[204:205]
	v_pk_mul_f32 v[206:207], v[198:199], v[206:207]
	v_pk_mul_f32 v[208:209], v[200:201], v[208:209]
	v_pk_mul_f32 v[202:203], v[202:203], v[238:239] op_sel_hi:[1,0]
	v_pk_mul_f32 v[204:205], v[204:205], v[238:239] op_sel_hi:[1,0]
	v_pk_mul_f32 v[206:207], v[206:207], v[238:239] op_sel_hi:[1,0]
	v_pk_mul_f32 v[208:209], v[208:209], v[238:239] op_sel_hi:[1,0]
	v_exp_f32_e32 v202, v202
	v_exp_f32_e32 v203, v203
	v_exp_f32_e32 v204, v204
	v_exp_f32_e32 v205, v205
	v_exp_f32_e32 v206, v206
	v_exp_f32_e32 v207, v207
	v_exp_f32_e32 v208, v208
	v_exp_f32_e32 v209, v209
	v_pk_add_f32 v[202:203], v[202:203], v[238:239] op_sel:[0,1] op_sel_hi:[1,1]
	v_pk_add_f32 v[204:205], v[204:205], v[238:239] op_sel:[0,1] op_sel_hi:[1,1]
	v_pk_add_f32 v[206:207], v[206:207], v[238:239] op_sel:[0,1] op_sel_hi:[1,1]
	v_pk_add_f32 v[208:209], v[208:209], v[238:239] op_sel:[0,1] op_sel_hi:[1,1]
	v_rcp_f32_e32 v202, v202
	v_rcp_f32_e32 v203, v203
	v_rcp_f32_e32 v204, v204
	v_rcp_f32_e32 v205, v205
	v_rcp_f32_e32 v206, v206
	v_rcp_f32_e32 v207, v207
	v_rcp_f32_e32 v208, v208
	v_rcp_f32_e32 v209, v209
	v_pk_mul_f32 v[194:195], v[194:195], v[202:203]
	v_pk_mul_f32 v[196:197], v[196:197], v[204:205]
	v_pk_mul_f32 v[198:199], v[198:199], v[206:207]
	v_pk_mul_f32 v[200:201], v[200:201], v[208:209]
	v_pk_mul_f32 v[150:151], v[150:151], v[194:195]
	v_pk_mul_f32 v[152:153], v[152:153], v[196:197]
	v_pk_mul_f32 v[146:147], v[146:147], v[198:199]
	v_pk_mul_f32 v[148:149], v[148:149], v[200:201]
	v_cvt_pk_bf16_f32 v150, v150, v151
	v_cvt_pk_bf16_f32 v151, v152, v153
	v_cvt_pk_bf16_f32 v152, v146, v147
	v_cvt_pk_bf16_f32 v153, v148, v149
	s_mov_b64 s[4:5], exec
	s_and_b64 exec, exec, s[42:43]
	global_store_dwordx4 v[192:193], v[150:153], off
	s_mov_b64 exec, s[4:5]
	v_pk_mul_f32 v[202:203], v[134:135], v[158:159]
	v_pk_mul_f32 v[204:205], v[136:137], v[160:161]
	v_pk_mul_f32 v[206:207], v[122:123], v[154:155]
	v_pk_mul_f32 v[208:209], v[124:125], v[156:157]
	s_mov_b64 s[6:7], 0x1800
	v_lshl_add_u64 v[234:235], v[192:193], 0, s[6:7]
	v_pk_fma_f32 v[202:203], v[78:79], v[130:131], v[202:203]
	v_pk_fma_f32 v[204:205], v[80:81], v[132:133], v[204:205]
	v_pk_fma_f32 v[206:207], v[62:63], v[118:119], v[206:207]
	v_pk_fma_f32 v[208:209], v[64:65], v[120:121], v[208:209]
	v_pk_fma_f32 v[194:195], v[82:83], v[110:111], v[202:203]
	v_pk_fma_f32 v[196:197], v[84:85], v[112:113], v[204:205]
	v_pk_fma_f32 v[198:199], v[66:67], v[102:103], v[206:207]
	v_pk_fma_f32 v[200:201], v[68:69], v[104:105], v[208:209]
	v_pk_mul_f32 v[202:203], v[194:195], v[236:237] op_sel_hi:[1,0]
	v_pk_mul_f32 v[204:205], v[196:197], v[236:237] op_sel_hi:[1,0]
	v_pk_mul_f32 v[206:207], v[198:199], v[236:237] op_sel_hi:[1,0]
	v_pk_mul_f32 v[208:209], v[200:201], v[236:237] op_sel_hi:[1,0]
	v_pk_fma_f32 v[202:203], v[194:195], v[202:203], v[236:237] op_sel:[0,0,1] op_sel_hi:[1,1,1]
	v_pk_fma_f32 v[204:205], v[196:197], v[204:205], v[236:237] op_sel:[0,0,1] op_sel_hi:[1,1,1]
	v_pk_fma_f32 v[206:207], v[198:199], v[206:207], v[236:237] op_sel:[0,0,1] op_sel_hi:[1,1,1]
	v_pk_fma_f32 v[208:209], v[200:201], v[208:209], v[236:237] op_sel:[0,0,1] op_sel_hi:[1,1,1]
	v_pk_mul_f32 v[202:203], v[194:195], v[202:203]
	v_pk_mul_f32 v[204:205], v[196:197], v[204:205]
	v_pk_mul_f32 v[206:207], v[198:199], v[206:207]
	v_pk_mul_f32 v[208:209], v[200:201], v[208:209]
	v_pk_mul_f32 v[202:203], v[202:203], v[238:239] op_sel_hi:[1,0]
	v_pk_mul_f32 v[204:205], v[204:205], v[238:239] op_sel_hi:[1,0]
	v_pk_mul_f32 v[206:207], v[206:207], v[238:239] op_sel_hi:[1,0]
	v_pk_mul_f32 v[208:209], v[208:209], v[238:239] op_sel_hi:[1,0]
	v_exp_f32_e32 v202, v202
	v_exp_f32_e32 v203, v203
	v_exp_f32_e32 v204, v204
	v_exp_f32_e32 v205, v205
	v_exp_f32_e32 v206, v206
	v_exp_f32_e32 v207, v207
	v_exp_f32_e32 v208, v208
	v_exp_f32_e32 v209, v209
	v_pk_add_f32 v[202:203], v[202:203], v[238:239] op_sel:[0,1] op_sel_hi:[1,1]
	v_pk_add_f32 v[204:205], v[204:205], v[238:239] op_sel:[0,1] op_sel_hi:[1,1]
; DEV u32x4 pack8(const float (&f)[8]) { u32x4 w; w.x = cvt_pk_bf16(f[0], f[1]); w.y = cvt_pk_bf16(f[2], f[3]); w.z = cvt_pk_bf16(f[4], f[5]); w.w = cvt_pk_bf16(f[6], f[7]); return w; }
; DEV float gelu_t(float x) { const float u = x * (0.7978845608f + 0.0356774081f * x * x); return x * __builtin_amdgcn_rcpf(1.f + __builtin_amdgcn_exp2f(-2.885390082f * u)); }
;     DEV bool operator()(f32x4 (&acc)[2][2][4][2], const Unit& u, int wr, int wc, int fr, int fq) const {
;     ...
;         for (int i = 0; i < 8; ++i) { float y[8];
; #pragma unroll
;             for (int c = 0; c < 8; ++c) {
;                 const float g0 = acc[i >> 2][0][i & 3][c >> 2][c & 3];
;                 const float gm1 = i >= 1 ? acc[(i - 1 < 0 ? 0 : i - 1) >> 2][0][(i - 1 < 0 ? 0 : i - 1) & 3][c >> 2][c & 3] : p7[c];
;                 const float gm2 = i >= 2 ? acc[(i - 2 < 0 ? 0 : i - 2) >> 2][0][(i - 2 < 0 ? 0 : i - 2) & 3][c >> 2][c & 3] : (i == 0 ? p6[c] : p7[c]);
;                 y[c] = gelu_t(w[0][c] * gm2 + w[1][c] * gm1 + w[2][c] * g0) * acc[i >> 2][1][i & 3][c >> 2][c & 3]; }
;             if (!(halo && i < 2)) *(u32x4*)(outp + (size_t)i * DFF) = pack8(y); }
	v_pk_add_f32 v[206:207], v[206:207], v[238:239] op_sel:[0,1] op_sel_hi:[1,1]
	v_pk_add_f32 v[208:209], v[208:209], v[238:239] op_sel:[0,1] op_sel_hi:[1,1]
	v_rcp_f32_e32 v202, v202
	v_rcp_f32_e32 v203, v203
	v_rcp_f32_e32 v204, v204
	v_rcp_f32_e32 v205, v205
	v_rcp_f32_e32 v206, v206
	v_rcp_f32_e32 v207, v207
	v_rcp_f32_e32 v208, v208
	v_rcp_f32_e32 v209, v209
	v_pk_mul_f32 v[194:195], v[194:195], v[202:203]
	v_pk_mul_f32 v[196:197], v[196:197], v[204:205]
	v_pk_mul_f32 v[198:199], v[198:199], v[206:207]
	v_pk_mul_f32 v[200:201], v[200:201], v[208:209]
	v_pk_mul_f32 v[142:143], v[142:143], v[194:195]
	v_pk_mul_f32 v[144:145], v[144:145], v[196:197]
	v_pk_mul_f32 v[138:139], v[138:139], v[198:199]
	v_pk_mul_f32 v[140:141], v[140:141], v[200:201]
	v_cvt_pk_bf16_f32 v142, v142, v143
	v_cvt_pk_bf16_f32 v143, v144, v145
	v_cvt_pk_bf16_f32 v144, v138, v139
	v_cvt_pk_bf16_f32 v145, v140, v141
	s_mov_b64 s[4:5], exec
	s_and_b64 exec, exec, s[42:43]
	global_store_dwordx4 v[234:235], v[142:145], off
	s_mov_b64 exec, s[4:5]
	v_pk_mul_f32 v[202:203], v[134:135], v[130:131]
	v_pk_mul_f32 v[204:205], v[136:137], v[132:133]
	v_pk_mul_f32 v[206:207], v[122:123], v[118:119]
	v_pk_mul_f32 v[208:209], v[124:125], v[120:121]
	s_mov_b64 s[6:7], 0x3000
	v_lshl_add_u64 v[232:233], v[192:193], 0, s[6:7]
	v_pk_fma_f32 v[202:203], v[78:79], v[110:111], v[202:203]
	v_pk_fma_f32 v[204:205], v[80:81], v[112:113], v[204:205]
	v_pk_fma_f32 v[206:207], v[62:63], v[102:103], v[206:207]
	v_pk_fma_f32 v[208:209], v[64:65], v[104:105], v[208:209]
	v_pk_fma_f32 v[194:195], v[82:83], v[94:95], v[202:203]
	v_pk_fma_f32 v[196:197], v[84:85], v[96:97], v[204:205]
	v_pk_fma_f32 v[198:199], v[66:67], v[86:87], v[206:207]
	v_pk_fma_f32 v[200:201], v[68:69], v[88:89], v[208:209]
	v_pk_mul_f32 v[202:203], v[194:195], v[236:237] op_sel_hi:[1,0]
	v_pk_mul_f32 v[204:205], v[196:197], v[236:237] op_sel_hi:[1,0]
	v_pk_mul_f32 v[206:207], v[198:199], v[236:237] op_sel_hi:[1,0]
	v_pk_mul_f32 v[208:209], v[200:201], v[236:237] op_sel_hi:[1,0]
	v_pk_fma_f32 v[202:203], v[194:195], v[202:203], v[236:237] op_sel:[0,0,1] op_sel_hi:[1,1,1]
	v_pk_fma_f32 v[204:205], v[196:197], v[204:205], v[236:237] op_sel:[0,0,1] op_sel_hi:[1,1,1]
	v_pk_fma_f32 v[206:207], v[198:199], v[206:207], v[236:237] op_sel:[0,0,1] op_sel_hi:[1,1,1]
	v_pk_fma_f32 v[208:209], v[200:201], v[208:209], v[236:237] op_sel:[0,0,1] op_sel_hi:[1,1,1]
	v_pk_mul_f32 v[202:203], v[194:195], v[202:203]
	v_pk_mul_f32 v[204:205], v[196:197], v[204:205]
	v_pk_mul_f32 v[206:207], v[198:199], v[206:207]
	v_pk_mul_f32 v[208:209], v[200:201], v[208:209]
	v_pk_mul_f32 v[202:203], v[202:203], v[238:239] op_sel_hi:[1,0]
	v_pk_mul_f32 v[204:205], v[204:205], v[238:239] op_sel_hi:[1,0]
	v_pk_mul_f32 v[206:207], v[206:207], v[238:239] op_sel_hi:[1,0]
	v_pk_mul_f32 v[208:209], v[208:209], v[238:239] op_sel_hi:[1,0]
	v_exp_f32_e32 v202, v202
	v_exp_f32_e32 v203, v203
	v_exp_f32_e32 v204, v204
	v_exp_f32_e32 v205, v205
	v_exp_f32_e32 v206, v206
	v_exp_f32_e32 v207, v207
	v_exp_f32_e32 v208, v208
	v_exp_f32_e32 v209, v209
	v_pk_add_f32 v[202:203], v[202:203], v[238:239] op_sel:[0,1] op_sel_hi:[1,1]
	v_pk_add_f32 v[204:205], v[204:205], v[238:239] op_sel:[0,1] op_sel_hi:[1,1]
	v_pk_add_f32 v[206:207], v[206:207], v[238:239] op_sel:[0,1] op_sel_hi:[1,1]
	v_pk_add_f32 v[208:209], v[208:209], v[238:239] op_sel:[0,1] op_sel_hi:[1,1]
	v_rcp_f32_e32 v202, v202
	v_rcp_f32_e32 v203, v203
	v_rcp_f32_e32 v204, v204
	v_rcp_f32_e32 v205, v205
	v_rcp_f32_e32 v206, v206
	v_rcp_f32_e32 v207, v207
	v_rcp_f32_e32 v208, v208
	v_rcp_f32_e32 v209, v209
	v_pk_mul_f32 v[194:195], v[194:195], v[202:203]
	v_pk_mul_f32 v[196:197], v[196:197], v[204:205]
	v_pk_mul_f32 v[198:199], v[198:199], v[206:207]
	v_pk_mul_f32 v[200:201], v[200:201], v[208:209]
	v_pk_mul_f32 v[126:127], v[126:127], v[194:195]
	v_pk_mul_f32 v[128:129], v[128:129], v[196:197]
	v_pk_mul_f32 v[114:115], v[114:115], v[198:199]
	v_pk_mul_f32 v[116:117], v[116:117], v[200:201]
	v_cvt_pk_bf16_f32 v126, v126, v127
	v_cvt_pk_bf16_f32 v127, v128, v129
	v_cvt_pk_bf16_f32 v128, v114, v115
	v_cvt_pk_bf16_f32 v129, v116, v117
	global_store_dwordx4 v[232:233], v[126:129], off
	v_pk_mul_f32 v[202:203], v[134:135], v[110:111]
	v_pk_mul_f32 v[204:205], v[136:137], v[112:113]
	v_pk_mul_f32 v[206:207], v[122:123], v[102:103]
	v_pk_mul_f32 v[208:209], v[124:125], v[104:105]
	s_mov_b64 s[6:7], 0x4800
	v_lshl_add_u64 v[234:235], v[192:193], 0, s[6:7]
	v_pk_fma_f32 v[202:203], v[78:79], v[94:95], v[202:203]
	v_pk_fma_f32 v[204:205], v[80:81], v[96:97], v[204:205]
	v_pk_fma_f32 v[206:207], v[62:63], v[86:87], v[206:207]
	v_pk_fma_f32 v[208:209], v[64:65], v[88:89], v[208:209]
	v_pk_fma_f32 v[194:195], v[82:83], v[70:71], v[202:203]
	v_pk_fma_f32 v[196:197], v[84:85], v[72:73], v[204:205]
	v_pk_fma_f32 v[198:199], v[66:67], v[54:55], v[206:207]
	v_pk_fma_f32 v[200:201], v[68:69], v[56:57], v[208:209]
	v_pk_mul_f32 v[202:203], v[194:195], v[236:237] op_sel_hi:[1,0]
	v_pk_mul_f32 v[204:205], v[196:197], v[236:237] op_sel_hi:[1,0]
	v_pk_mul_f32 v[206:207], v[198:199], v[236:237] op_sel_hi:[1,0]
	v_pk_mul_f32 v[208:209], v[200:201], v[236:237] op_sel_hi:[1,0]
	v_pk_fma_f32 v[202:203], v[194:195], v[202:203], v[236:237] op_sel:[0,0,1] op_sel_hi:[1,1,1]
	v_pk_fma_f32 v[204:205], v[196:197], v[204:205], v[236:237] op_sel:[0,0,1] op_sel_hi:[1,1,1]
	v_pk_fma_f32 v[206:207], v[198:199], v[206:207], v[236:237] op_sel:[0,0,1] op_sel_hi:[1,1,1]
	v_pk_fma_f32 v[208:209], v[200:201], v[208:209], v[236:237] op_sel:[0,0,1] op_sel_hi:[1,1,1]
	v_pk_mul_f32 v[202:203], v[194:195], v[202:203]
	v_pk_mul_f32 v[204:205], v[196:197], v[204:205]
; DEV u32x4 pack8(const float (&f)[8]) { u32x4 w; w.x = cvt_pk_bf16(f[0], f[1]); w.y = cvt_pk_bf16(f[2], f[3]); w.z = cvt_pk_bf16(f[4], f[5]); w.w = cvt_pk_bf16(f[6], f[7]); return w; }
; DEV float gelu_t(float x) { const float u = x * (0.7978845608f + 0.0356774081f * x * x); return x * __builtin_amdgcn_rcpf(1.f + __builtin_amdgcn_exp2f(-2.885390082f * u)); }
;     DEV bool operator()(f32x4 (&acc)[2][2][4][2], const Unit& u, int wr, int wc, int fr, int fq) const {
;     ...
;         for (int i = 0; i < 8; ++i) { float y[8];
; #pragma unroll
;             for (int c = 0; c < 8; ++c) {
;                 const float g0 = acc[i >> 2][0][i & 3][c >> 2][c & 3];
;                 const float gm1 = i >= 1 ? acc[(i - 1 < 0 ? 0 : i - 1) >> 2][0][(i - 1 < 0 ? 0 : i - 1) & 3][c >> 2][c & 3] : p7[c];
;                 const float gm2 = i >= 2 ? acc[(i - 2 < 0 ? 0 : i - 2) >> 2][0][(i - 2 < 0 ? 0 : i - 2) & 3][c >> 2][c & 3] : (i == 0 ? p6[c] : p7[c]);
;                 y[c] = gelu_t(w[0][c] * gm2 + w[1][c] * gm1 + w[2][c] * g0) * acc[i >> 2][1][i & 3][c >> 2][c & 3]; }
;             if (!(halo && i < 2)) *(u32x4*)(outp + (size_t)i * DFF) = pack8(y); }
	v_pk_mul_f32 v[206:207], v[198:199], v[206:207]
	v_pk_mul_f32 v[208:209], v[200:201], v[208:209]
	v_pk_mul_f32 v[202:203], v[202:203], v[238:239] op_sel_hi:[1,0]
	v_pk_mul_f32 v[204:205], v[204:205], v[238:239] op_sel_hi:[1,0]
	v_pk_mul_f32 v[206:207], v[206:207], v[238:239] op_sel_hi:[1,0]
	v_pk_mul_f32 v[208:209], v[208:209], v[238:239] op_sel_hi:[1,0]
	v_exp_f32_e32 v202, v202
	v_exp_f32_e32 v203, v203
	v_exp_f32_e32 v204, v204
	v_exp_f32_e32 v205, v205
	v_exp_f32_e32 v206, v206
	v_exp_f32_e32 v207, v207
	v_exp_f32_e32 v208, v208
	v_exp_f32_e32 v209, v209
	v_pk_add_f32 v[202:203], v[202:203], v[238:239] op_sel:[0,1] op_sel_hi:[1,1]
	v_pk_add_f32 v[204:205], v[204:205], v[238:239] op_sel:[0,1] op_sel_hi:[1,1]
	v_pk_add_f32 v[206:207], v[206:207], v[238:239] op_sel:[0,1] op_sel_hi:[1,1]
	v_pk_add_f32 v[208:209], v[208:209], v[238:239] op_sel:[0,1] op_sel_hi:[1,1]
	v_rcp_f32_e32 v202, v202
	v_rcp_f32_e32 v203, v203
	v_rcp_f32_e32 v204, v204
	v_rcp_f32_e32 v205, v205
	v_rcp_f32_e32 v206, v206
	v_rcp_f32_e32 v207, v207
	v_rcp_f32_e32 v208, v208
	v_rcp_f32_e32 v209, v209
	v_pk_mul_f32 v[194:195], v[194:195], v[202:203]
	v_pk_mul_f32 v[196:197], v[196:197], v[204:205]
	v_pk_mul_f32 v[198:199], v[198:199], v[206:207]
	v_pk_mul_f32 v[200:201], v[200:201], v[208:209]
	v_pk_mul_f32 v[106:107], v[106:107], v[194:195]
	v_pk_mul_f32 v[108:109], v[108:109], v[196:197]
	v_pk_mul_f32 v[98:99], v[98:99], v[198:199]
	v_pk_mul_f32 v[100:101], v[100:101], v[200:201]
	v_cvt_pk_bf16_f32 v106, v106, v107
	v_cvt_pk_bf16_f32 v107, v108, v109
	v_cvt_pk_bf16_f32 v108, v98, v99
	v_cvt_pk_bf16_f32 v109, v100, v101
	global_store_dwordx4 v[234:235], v[106:109], off
	v_pk_mul_f32 v[202:203], v[134:135], v[94:95]
	v_pk_mul_f32 v[204:205], v[136:137], v[96:97]
	v_pk_mul_f32 v[206:207], v[122:123], v[86:87]
	v_pk_mul_f32 v[208:209], v[124:125], v[88:89]
	s_mov_b64 s[6:7], 0x6000
	v_lshl_add_u64 v[232:233], v[192:193], 0, s[6:7]
	v_pk_fma_f32 v[202:203], v[78:79], v[70:71], v[202:203]
	v_pk_fma_f32 v[204:205], v[80:81], v[72:73], v[204:205]
	v_pk_fma_f32 v[206:207], v[62:63], v[54:55], v[206:207]
	v_pk_fma_f32 v[208:209], v[64:65], v[56:57], v[208:209]
	v_pk_fma_f32 v[194:195], v[82:83], v[46:47], v[202:203]
	v_pk_fma_f32 v[196:197], v[84:85], v[48:49], v[204:205]
	v_pk_fma_f32 v[198:199], v[66:67], v[38:39], v[206:207]
	v_pk_fma_f32 v[200:201], v[68:69], v[40:41], v[208:209]
	v_pk_mul_f32 v[202:203], v[194:195], v[236:237] op_sel_hi:[1,0]
	v_pk_mul_f32 v[204:205], v[196:197], v[236:237] op_sel_hi:[1,0]
	v_pk_mul_f32 v[206:207], v[198:199], v[236:237] op_sel_hi:[1,0]
	v_pk_mul_f32 v[208:209], v[200:201], v[236:237] op_sel_hi:[1,0]
	v_pk_fma_f32 v[202:203], v[194:195], v[202:203], v[236:237] op_sel:[0,0,1] op_sel_hi:[1,1,1]
	v_pk_fma_f32 v[204:205], v[196:197], v[204:205], v[236:237] op_sel:[0,0,1] op_sel_hi:[1,1,1]
	v_pk_fma_f32 v[206:207], v[198:199], v[206:207], v[236:237] op_sel:[0,0,1] op_sel_hi:[1,1,1]
	v_pk_fma_f32 v[208:209], v[200:201], v[208:209], v[236:237] op_sel:[0,0,1] op_sel_hi:[1,1,1]
	v_pk_mul_f32 v[202:203], v[194:195], v[202:203]
	v_pk_mul_f32 v[204:205], v[196:197], v[204:205]
	v_pk_mul_f32 v[206:207], v[198:199], v[206:207]
	v_pk_mul_f32 v[208:209], v[200:201], v[208:209]
	v_pk_mul_f32 v[202:203], v[202:203], v[238:239] op_sel_hi:[1,0]
	v_pk_mul_f32 v[204:205], v[204:205], v[238:239] op_sel_hi:[1,0]
	v_pk_mul_f32 v[206:207], v[206:207], v[238:239] op_sel_hi:[1,0]
	v_pk_mul_f32 v[208:209], v[208:209], v[238:239] op_sel_hi:[1,0]
	v_exp_f32_e32 v202, v202
	v_exp_f32_e32 v203, v203
	v_exp_f32_e32 v204, v204
	v_exp_f32_e32 v205, v205
	v_exp_f32_e32 v206, v206
	v_exp_f32_e32 v207, v207
	v_exp_f32_e32 v208, v208
	v_exp_f32_e32 v209, v209
	v_pk_add_f32 v[202:203], v[202:203], v[238:239] op_sel:[0,1] op_sel_hi:[1,1]
	v_pk_add_f32 v[204:205], v[204:205], v[238:239] op_sel:[0,1] op_sel_hi:[1,1]
	v_pk_add_f32 v[206:207], v[206:207], v[238:239] op_sel:[0,1] op_sel_hi:[1,1]
	v_pk_add_f32 v[208:209], v[208:209], v[238:239] op_sel:[0,1] op_sel_hi:[1,1]
	v_rcp_f32_e32 v202, v202
	v_rcp_f32_e32 v203, v203
	v_rcp_f32_e32 v204, v204
	v_rcp_f32_e32 v205, v205
	v_rcp_f32_e32 v206, v206
	v_rcp_f32_e32 v207, v207
	v_rcp_f32_e32 v208, v208
	v_rcp_f32_e32 v209, v209
	v_pk_mul_f32 v[194:195], v[194:195], v[202:203]
	v_pk_mul_f32 v[196:197], v[196:197], v[204:205]
	v_pk_mul_f32 v[198:199], v[198:199], v[206:207]
	v_pk_mul_f32 v[200:201], v[200:201], v[208:209]
	v_pk_mul_f32 v[90:91], v[90:91], v[194:195]
	v_pk_mul_f32 v[92:93], v[92:93], v[196:197]
	v_pk_mul_f32 v[74:75], v[74:75], v[198:199]
	v_pk_mul_f32 v[76:77], v[76:77], v[200:201]
	v_cvt_pk_bf16_f32 v90, v90, v91
	v_cvt_pk_bf16_f32 v91, v92, v93
	v_cvt_pk_bf16_f32 v92, v74, v75
	v_cvt_pk_bf16_f32 v93, v76, v77
	global_store_dwordx4 v[232:233], v[90:93], off
	v_pk_mul_f32 v[202:203], v[134:135], v[70:71]
	v_pk_mul_f32 v[204:205], v[136:137], v[72:73]
	v_pk_mul_f32 v[206:207], v[122:123], v[54:55]
	v_pk_mul_f32 v[208:209], v[124:125], v[56:57]
	s_mov_b64 s[6:7], 0x7800
	v_lshl_add_u64 v[234:235], v[192:193], 0, s[6:7]
	v_pk_fma_f32 v[202:203], v[78:79], v[46:47], v[202:203]
	v_pk_fma_f32 v[204:205], v[80:81], v[48:49], v[204:205]
	v_pk_fma_f32 v[206:207], v[62:63], v[38:39], v[206:207]
	v_pk_fma_f32 v[208:209], v[64:65], v[40:41], v[208:209]
	v_pk_fma_f32 v[194:195], v[82:83], v[30:31], v[202:203]
	v_pk_fma_f32 v[196:197], v[84:85], v[32:33], v[204:205]
	v_pk_fma_f32 v[198:199], v[66:67], v[14:15], v[206:207]
	v_pk_fma_f32 v[200:201], v[68:69], v[16:17], v[208:209]
	v_pk_mul_f32 v[202:203], v[194:195], v[236:237] op_sel_hi:[1,0]
	v_pk_mul_f32 v[204:205], v[196:197], v[236:237] op_sel_hi:[1,0]
; DEV u32x4 pack8(const float (&f)[8]) { u32x4 w; w.x = cvt_pk_bf16(f[0], f[1]); w.y = cvt_pk_bf16(f[2], f[3]); w.z = cvt_pk_bf16(f[4], f[5]); w.w = cvt_pk_bf16(f[6], f[7]); return w; }
; DEV float gelu_t(float x) { const float u = x * (0.7978845608f + 0.0356774081f * x * x); return x * __builtin_amdgcn_rcpf(1.f + __builtin_amdgcn_exp2f(-2.885390082f * u)); }
;     DEV bool operator()(f32x4 (&acc)[2][2][4][2], const Unit& u, int wr, int wc, int fr, int fq) const {
;     ...
;         for (int i = 0; i < 8; ++i) { float y[8];
; #pragma unroll
;             for (int c = 0; c < 8; ++c) {
;                 const float g0 = acc[i >> 2][0][i & 3][c >> 2][c & 3];
;                 const float gm1 = i >= 1 ? acc[(i - 1 < 0 ? 0 : i - 1) >> 2][0][(i - 1 < 0 ? 0 : i - 1) & 3][c >> 2][c & 3] : p7[c];
;                 const float gm2 = i >= 2 ? acc[(i - 2 < 0 ? 0 : i - 2) >> 2][0][(i - 2 < 0 ? 0 : i - 2) & 3][c >> 2][c & 3] : (i == 0 ? p6[c] : p7[c]);
;                 y[c] = gelu_t(w[0][c] * gm2 + w[1][c] * gm1 + w[2][c] * g0) * acc[i >> 2][1][i & 3][c >> 2][c & 3]; }
;             if (!(halo && i < 2)) *(u32x4*)(outp + (size_t)i * DFF) = pack8(y); }
	v_pk_mul_f32 v[206:207], v[198:199], v[236:237] op_sel_hi:[1,0]
	v_pk_mul_f32 v[208:209], v[200:201], v[236:237] op_sel_hi:[1,0]
	v_pk_fma_f32 v[202:203], v[194:195], v[202:203], v[236:237] op_sel:[0,0,1] op_sel_hi:[1,1,1]
	v_pk_fma_f32 v[204:205], v[196:197], v[204:205], v[236:237] op_sel:[0,0,1] op_sel_hi:[1,1,1]
	v_pk_fma_f32 v[206:207], v[198:199], v[206:207], v[236:237] op_sel:[0,0,1] op_sel_hi:[1,1,1]
	v_pk_fma_f32 v[208:209], v[200:201], v[208:209], v[236:237] op_sel:[0,0,1] op_sel_hi:[1,1,1]
	v_pk_mul_f32 v[202:203], v[194:195], v[202:203]
	v_pk_mul_f32 v[204:205], v[196:197], v[204:205]
	v_pk_mul_f32 v[206:207], v[198:199], v[206:207]
	v_pk_mul_f32 v[208:209], v[200:201], v[208:209]
	v_pk_mul_f32 v[202:203], v[202:203], v[238:239] op_sel_hi:[1,0]
	v_pk_mul_f32 v[204:205], v[204:205], v[238:239] op_sel_hi:[1,0]
	v_pk_mul_f32 v[206:207], v[206:207], v[238:239] op_sel_hi:[1,0]
	v_pk_mul_f32 v[208:209], v[208:209], v[238:239] op_sel_hi:[1,0]
	v_exp_f32_e32 v202, v202
	v_exp_f32_e32 v203, v203
	v_exp_f32_e32 v204, v204
	v_exp_f32_e32 v205, v205
	v_exp_f32_e32 v206, v206
	v_exp_f32_e32 v207, v207
	v_exp_f32_e32 v208, v208
	v_exp_f32_e32 v209, v209
	v_pk_add_f32 v[202:203], v[202:203], v[238:239] op_sel:[0,1] op_sel_hi:[1,1]
	v_pk_add_f32 v[204:205], v[204:205], v[238:239] op_sel:[0,1] op_sel_hi:[1,1]
	v_pk_add_f32 v[206:207], v[206:207], v[238:239] op_sel:[0,1] op_sel_hi:[1,1]
	v_pk_add_f32 v[208:209], v[208:209], v[238:239] op_sel:[0,1] op_sel_hi:[1,1]
	v_rcp_f32_e32 v202, v202
	v_rcp_f32_e32 v203, v203
	v_rcp_f32_e32 v204, v204
	v_rcp_f32_e32 v205, v205
	v_rcp_f32_e32 v206, v206
	v_rcp_f32_e32 v207, v207
	v_rcp_f32_e32 v208, v208
	v_rcp_f32_e32 v209, v209
	v_pk_mul_f32 v[194:195], v[194:195], v[202:203]
	v_pk_mul_f32 v[196:197], v[196:197], v[204:205]
	v_pk_mul_f32 v[198:199], v[198:199], v[206:207]
	v_pk_mul_f32 v[200:201], v[200:201], v[208:209]
	v_pk_mul_f32 v[58:59], v[58:59], v[194:195]
	v_pk_mul_f32 v[60:61], v[60:61], v[196:197]
	v_pk_mul_f32 v[50:51], v[50:51], v[198:199]
	v_pk_mul_f32 v[52:53], v[52:53], v[200:201]
	v_cvt_pk_bf16_f32 v58, v58, v59
	v_cvt_pk_bf16_f32 v59, v60, v61
	v_cvt_pk_bf16_f32 v60, v50, v51
	v_cvt_pk_bf16_f32 v61, v52, v53
	global_store_dwordx4 v[234:235], v[58:61], off
	v_pk_mul_f32 v[202:203], v[134:135], v[46:47]
	v_pk_mul_f32 v[204:205], v[136:137], v[48:49]
	v_pk_mul_f32 v[206:207], v[122:123], v[38:39]
	v_pk_mul_f32 v[208:209], v[124:125], v[40:41]
	s_mov_b64 s[6:7], 0x9000
	v_lshl_add_u64 v[232:233], v[192:193], 0, s[6:7]
	v_pk_fma_f32 v[202:203], v[78:79], v[30:31], v[202:203]
	v_pk_fma_f32 v[204:205], v[80:81], v[32:33], v[204:205]
	v_pk_fma_f32 v[206:207], v[62:63], v[14:15], v[206:207]
	v_pk_fma_f32 v[208:209], v[64:65], v[16:17], v[208:209]
	v_pk_fma_f32 v[194:195], v[82:83], v[26:27], v[202:203]
	v_pk_fma_f32 v[196:197], v[84:85], v[28:29], v[204:205]
	v_pk_fma_f32 v[198:199], v[66:67], v[10:11], v[206:207]
	v_pk_fma_f32 v[200:201], v[68:69], v[12:13], v[208:209]
	v_pk_mul_f32 v[202:203], v[194:195], v[236:237] op_sel_hi:[1,0]
	v_pk_mul_f32 v[204:205], v[196:197], v[236:237] op_sel_hi:[1,0]
	v_pk_mul_f32 v[206:207], v[198:199], v[236:237] op_sel_hi:[1,0]
	v_pk_mul_f32 v[208:209], v[200:201], v[236:237] op_sel_hi:[1,0]
	v_pk_fma_f32 v[202:203], v[194:195], v[202:203], v[236:237] op_sel:[0,0,1] op_sel_hi:[1,1,1]
	v_pk_fma_f32 v[204:205], v[196:197], v[204:205], v[236:237] op_sel:[0,0,1] op_sel_hi:[1,1,1]
	v_pk_fma_f32 v[206:207], v[198:199], v[206:207], v[236:237] op_sel:[0,0,1] op_sel_hi:[1,1,1]
	v_pk_fma_f32 v[208:209], v[200:201], v[208:209], v[236:237] op_sel:[0,0,1] op_sel_hi:[1,1,1]
	v_pk_mul_f32 v[202:203], v[194:195], v[202:203]
	v_pk_mul_f32 v[204:205], v[196:197], v[204:205]
	v_pk_mul_f32 v[206:207], v[198:199], v[206:207]
	v_pk_mul_f32 v[208:209], v[200:201], v[208:209]
	v_pk_mul_f32 v[202:203], v[202:203], v[238:239] op_sel_hi:[1,0]
	v_pk_mul_f32 v[204:205], v[204:205], v[238:239] op_sel_hi:[1,0]
	v_pk_mul_f32 v[206:207], v[206:207], v[238:239] op_sel_hi:[1,0]
	v_pk_mul_f32 v[208:209], v[208:209], v[238:239] op_sel_hi:[1,0]
	v_exp_f32_e32 v202, v202
	v_exp_f32_e32 v203, v203
	v_exp_f32_e32 v204, v204
	v_exp_f32_e32 v205, v205
	v_exp_f32_e32 v206, v206
	v_exp_f32_e32 v207, v207
	v_exp_f32_e32 v208, v208
	v_exp_f32_e32 v209, v209
	v_pk_add_f32 v[202:203], v[202:203], v[238:239] op_sel:[0,1] op_sel_hi:[1,1]
; DEV float gelu_t(float x) { const float u = x * (0.7978845608f + 0.0356774081f * x * x); return x * __builtin_amdgcn_rcpf(1.f + __builtin_amdgcn_exp2f(-2.885390082f * u)); }
; DEV u32x4 pack8(const float (&f)[8]) { u32x4 w; w.x = cvt_pk_bf16(f[0], f[1]); w.y = cvt_pk_bf16(f[2], f[3]); w.z = cvt_pk_bf16(f[4], f[5]); w.w = cvt_pk_bf16(f[6], f[7]); return w; }
; #define PG8_BAR __builtin_amdgcn_s_barrier()
;     DEV bool operator()(f32x4 (&acc)[2][2][4][2], const Unit& u, int wr, int wc, int fr, int fq) const {
;     ...
;         for (int i = 0; i < 8; ++i) { float y[8];
; #pragma unroll
;             for (int c = 0; c < 8; ++c) {
;                 const float g0 = acc[i >> 2][0][i & 3][c >> 2][c & 3];
;                 const float gm1 = i >= 1 ? acc[(i - 1 < 0 ? 0 : i - 1) >> 2][0][(i - 1 < 0 ? 0 : i - 1) & 3][c >> 2][c & 3] : p7[c];
;                 const float gm2 = i >= 2 ? acc[(i - 2 < 0 ? 0 : i - 2) >> 2][0][(i - 2 < 0 ? 0 : i - 2) & 3][c >> 2][c & 3] : (i == 0 ? p6[c] : p7[c]);
;                 y[c] = gelu_t(w[0][c] * gm2 + w[1][c] * gm1 + w[2][c] * g0) * acc[i >> 2][1][i & 3][c >> 2][c & 3]; }
;             if (!(halo && i < 2)) *(u32x4*)(outp + (size_t)i * DFF) = pack8(y); }
; template <bool ALIGN_EPI, class Epi, class Sched>
; DEV void gemm_phase(LAS unsigned char* lds, const Gemm g, const Sched& S, const Epi& E) {
;     ...
;         if (ALIGN_EPI) { if (wr == 0) PG8_BAR; }
;         const bool rst = E(acc, cur, wr, wc, fr, fq);
;         if (!has_next) break;
;         if (rst) {
; #pragma unroll
;         for (int a = 0; a < 2; ++a)
; #pragma unroll
;             for (int b = 0; b < 2; ++b)
; #pragma unroll
;                 for (int m = 0; m < 4; ++m)
; #pragma unroll
;                     for (int n = 0; n < 2; ++n) acc[a][b][m][n] = (f32x4){0.f, 0.f, 0.f, 0.f}; }
;         cur = nxt; cA = nA; cB = nB; ++ui;
;         if (ALIGN_EPI) { if (wr == 1) PG8_BAR; }
	v_pk_add_f32 v[204:205], v[204:205], v[238:239] op_sel:[0,1] op_sel_hi:[1,1]
	v_pk_add_f32 v[206:207], v[206:207], v[238:239] op_sel:[0,1] op_sel_hi:[1,1]
	v_pk_add_f32 v[208:209], v[208:209], v[238:239] op_sel:[0,1] op_sel_hi:[1,1]
	v_rcp_f32_e32 v202, v202
	v_rcp_f32_e32 v203, v203
	v_rcp_f32_e32 v204, v204
	v_rcp_f32_e32 v205, v205
	v_rcp_f32_e32 v206, v206
	v_rcp_f32_e32 v207, v207
	v_rcp_f32_e32 v208, v208
	v_rcp_f32_e32 v209, v209
	v_pk_mul_f32 v[194:195], v[194:195], v[202:203]
	v_pk_mul_f32 v[196:197], v[196:197], v[204:205]
	v_pk_mul_f32 v[198:199], v[198:199], v[206:207]
	v_pk_mul_f32 v[200:201], v[200:201], v[208:209]
	v_pk_mul_f32 v[42:43], v[42:43], v[194:195]
	v_pk_mul_f32 v[44:45], v[44:45], v[196:197]
	v_pk_mul_f32 v[34:35], v[34:35], v[198:199]
	v_pk_mul_f32 v[36:37], v[36:37], v[200:201]
	v_cvt_pk_bf16_f32 v42, v42, v43
	v_cvt_pk_bf16_f32 v43, v44, v45
	v_cvt_pk_bf16_f32 v44, v34, v35
	v_cvt_pk_bf16_f32 v45, v36, v37
	global_store_dwordx4 v[232:233], v[42:45], off
	v_pk_mul_f32 v[202:203], v[134:135], v[30:31]
	v_pk_mul_f32 v[204:205], v[136:137], v[32:33]
	v_pk_mul_f32 v[206:207], v[122:123], v[14:15]
	v_pk_mul_f32 v[208:209], v[124:125], v[16:17]
	s_mov_b64 s[6:7], 0xa800
	v_lshl_add_u64 v[234:235], v[192:193], 0, s[6:7]
	v_pk_fma_f32 v[202:203], v[78:79], v[26:27], v[202:203]
	v_pk_fma_f32 v[204:205], v[80:81], v[28:29], v[204:205]
	v_pk_fma_f32 v[206:207], v[62:63], v[10:11], v[206:207]
	v_pk_fma_f32 v[208:209], v[64:65], v[12:13], v[208:209]
	v_pk_fma_f32 v[194:195], v[82:83], v[22:23], v[202:203]
	v_pk_fma_f32 v[196:197], v[84:85], v[24:25], v[204:205]
	v_pk_fma_f32 v[198:199], v[66:67], v[6:7], v[206:207]
	v_pk_fma_f32 v[200:201], v[68:69], v[8:9], v[208:209]
	v_pk_mul_f32 v[202:203], v[194:195], v[236:237] op_sel_hi:[1,0]
	v_pk_mul_f32 v[204:205], v[196:197], v[236:237] op_sel_hi:[1,0]
	v_pk_mul_f32 v[206:207], v[198:199], v[236:237] op_sel_hi:[1,0]
	v_pk_mul_f32 v[208:209], v[200:201], v[236:237] op_sel_hi:[1,0]
	v_pk_fma_f32 v[202:203], v[194:195], v[202:203], v[236:237] op_sel:[0,0,1] op_sel_hi:[1,1,1]
	v_pk_fma_f32 v[204:205], v[196:197], v[204:205], v[236:237] op_sel:[0,0,1] op_sel_hi:[1,1,1]
	v_pk_fma_f32 v[206:207], v[198:199], v[206:207], v[236:237] op_sel:[0,0,1] op_sel_hi:[1,1,1]
	v_pk_fma_f32 v[208:209], v[200:201], v[208:209], v[236:237] op_sel:[0,0,1] op_sel_hi:[1,1,1]
	v_pk_mul_f32 v[202:203], v[194:195], v[202:203]
	v_pk_mul_f32 v[204:205], v[196:197], v[204:205]
	v_pk_mul_f32 v[206:207], v[198:199], v[206:207]
	v_pk_mul_f32 v[208:209], v[200:201], v[208:209]
	v_pk_mul_f32 v[202:203], v[202:203], v[238:239] op_sel_hi:[1,0]
	v_pk_mul_f32 v[204:205], v[204:205], v[238:239] op_sel_hi:[1,0]
	v_pk_mul_f32 v[206:207], v[206:207], v[238:239] op_sel_hi:[1,0]
	v_pk_mul_f32 v[208:209], v[208:209], v[238:239] op_sel_hi:[1,0]
	v_exp_f32_e32 v202, v202
	v_exp_f32_e32 v203, v203
	v_exp_f32_e32 v204, v204
	v_exp_f32_e32 v205, v205
	v_exp_f32_e32 v206, v206
	v_exp_f32_e32 v207, v207
	v_exp_f32_e32 v208, v208
	v_exp_f32_e32 v209, v209
	v_pk_add_f32 v[202:203], v[202:203], v[238:239] op_sel:[0,1] op_sel_hi:[1,1]
	v_pk_add_f32 v[204:205], v[204:205], v[238:239] op_sel:[0,1] op_sel_hi:[1,1]
	v_pk_add_f32 v[206:207], v[206:207], v[238:239] op_sel:[0,1] op_sel_hi:[1,1]
	v_pk_add_f32 v[208:209], v[208:209], v[238:239] op_sel:[0,1] op_sel_hi:[1,1]
	v_rcp_f32_e32 v202, v202
	v_rcp_f32_e32 v203, v203
	v_rcp_f32_e32 v204, v204
	v_rcp_f32_e32 v205, v205
	v_rcp_f32_e32 v206, v206
	v_rcp_f32_e32 v207, v207
	v_rcp_f32_e32 v208, v208
	v_rcp_f32_e32 v209, v209
	v_pk_mul_f32 v[194:195], v[194:195], v[202:203]
	v_pk_mul_f32 v[196:197], v[196:197], v[204:205]
	v_pk_mul_f32 v[198:199], v[198:199], v[206:207]
	v_pk_mul_f32 v[200:201], v[200:201], v[208:209]
	v_pk_mul_f32 v[18:19], v[18:19], v[194:195]
	v_pk_mul_f32 v[20:21], v[20:21], v[196:197]
	v_pk_mul_f32 v[2:3], v[2:3], v[198:199]
	v_pk_mul_f32 v[4:5], v[4:5], v[200:201]
	v_cvt_pk_bf16_f32 v18, v18, v19
	v_cvt_pk_bf16_f32 v19, v20, v21
	v_cvt_pk_bf16_f32 v20, v2, v3
	v_cvt_pk_bf16_f32 v21, v4, v5
	global_store_dwordx4 v[234:235], v[18:21], off
	s_mov_b64 s[4:5], -1
	s_andn2_b64 vcc, exec, s[44:45]
	s_cbranch_vccnz .LBB0_24
	v_readlane_b32 s4, v255, 4
	v_readlane_b32 s5, v255, 5
	s_andn2_b64 vcc, exec, s[4:5]
	s_cbranch_vccnz .LBB0_23
	s_barrier
	s_branch .LBB0_23
